# ticket-atomic wait deferred to prologue vmcnt; DN scan waves at setprio 2
# speedup vs baseline: 1.0037x; 1.0037x over previous
; __device__ __forceinline__ int otid() { int t = threadIdx.x; asm volatile("" : "+v"(t)); return t; }
; __device__ __forceinline__ void phase_mixers(const Params& p, int l, char* smem, bool scans_only) {
;     ...
;   for (int it = 0;; ++it) {
;     int t;
;     if (it == 0 && first >= 0) t = first;
;     else {
;       if (otid() == 0) *s_taskp = atomicAdd(ctr, 1) + (full ? n_scan : 0);
;       __syncthreads();
;       t = *s_taskp;
;       __syncthreads();
;     }
;     if (t >= total) break;
;     if (t < n_dn) dn_task(p, l, t, smem);
;     else if (t < n_dn + n_hg) hg_task(p, l, t - n_dn, smem);
;     else if (t < n_scan) s5_task(p, l, t - n_dn - n_hg, smem);
;     else { const bool ic = t >= n_scan + n_al; attn_task(p, l, t - n_scan - (ic ? n_al : 0), ic, smem); }
;     __syncthreads();
.LBB0_105:
	s_setprio 0
	s_add_i32 s80, s80, 1
	s_mov_b64 s[40:41], 0
	s_mov_b64 s[82:83], s[30:31]
	s_mov_b32 s84, 0x18000
	s_waitcnt vmcnt(0)
	s_barrier

; __device__ __forceinline__ void dn_task(const Params& p, int l, int task, char* smem) {
;     ...
;   const int dir = task & 1, hd = (task >> 1) & 3, vh = (task >> 3) & 1, b = task >> 4;
;   float* qs = (float*)smem;
;   float* ks = qs + 32 * 68;
;   float* vs = ks + 32 * 68;
;   float* al = vs + 32 * 64;
;   float* dots = al + 64;
;   float* wl = al + 128;
;   bf16_t* rawb = (bf16_t*)(wl + 5 * 192);
;   const bf16_t* P = WS_BF(p, OFF_P);
;   const float* cw = p.in[11] + (size_t)l * 5 * 768;
;   const float Aexp = __expf(p.in[12][l * 8 + dir * 4 + hd]);
;   const float dtb = p.in[13][l * 8 + dir * 4 + hd];
;   bf16_t* O = WS_BF(p, OFF_SC) + (size_t)dir * NTOK * 256;
;   const int v = vh * 32 + (tid >> 3), kq = tid & 7;
;   for (int i = tid; i < 5 * 192; i += 256) {
;     const int j = i / 192, c = i - j * 192;
;     wl[i] = cw[j * 768 + (c >> 6) * 256 + hd * 64 + (c & 63)];
.LBB0_161:
	s_mov_b64 s[30:31], s[82:83]
	s_andn2_b64 vcc, exec, s[40:41]
	s_cbranch_vccnz .LBB0_105
	s_setprio 2
	s_and_b32 s54, s60, 1
	s_lshl_b32 s56, s54, 2
	v_readlane_b32 s2, v250, 38
	s_bfe_u32 s55, s60, 0x20001
	s_or_b32 s40, s56, s2
	s_or_b32 s40, s40, s55
	s_lshl_b32 s40, s40, 2
	v_mov_b32_e32 v0, s40
	s_load_dwordx16 s[36:51], s[0:1], 0x58
	v_mov_b32_e32 v138, v172
	s_waitcnt lgkmcnt(0)
	global_load_dword v6, v0, s[38:39]
	global_load_dword v160, v0, s[40:41]
	s_movk_i32 s40, 0x3c0
	v_cmp_gt_i32_e32 vcc, s40, v138
	s_lshl_b32 s61, s55, 6
	s_and_saveexec_b64 s[40:41], vcc
	s_cbranch_execz .LBB0_179
	v_max_i32_e32 v0, 0x2c0, v138
	v_sub_u32_e32 v0, v0, v138
	s_waitcnt vmcnt(0)
	v_add_u32_e32 v2, 0xff, v0
	s_movk_i32 s42, 0xff
	v_and_b32_e32 v4, 63, v138
	v_cmp_lt_u32_e32 vcc, s42, v2
	s_mov_b64 s[44:45], 0
	s_and_saveexec_b64 s[42:43], vcc
	s_xor_b64 s[42:43], exec, s[42:43]
	s_cbranch_execnz .LBB0_173
	s_andn2_saveexec_b64 s[42:43], s[42:43]
	s_cbranch_execnz .LBB0_176

; __device__ __forceinline__ int otid() { int t = threadIdx.x; asm volatile("" : "+v"(t)); return t; }
; __device__ __forceinline__ int frag_off(int fr, int fq) { return (fr >> 3) * 1024 + (fr & 7) * 128 + ((fq ^ ((fr >> 1) & 7)) << 4); }
;   const int tid = otid(), lane = tid & 63, wid = tid >> 6, wr = wid >> 1, wc = wid & 1, fr = lane & 15, fq = lane >> 4;
;   const int o0 = tid * 16;
;   const int lrow = (o0 >> 10) * 8 + ((o0 >> 7) & 7), lcol = ((((o0 >> 4) & 7) ^ ((lrow >> 1) & 7))) * 8;
;   const bf16_t* ag = A + (size_t)lrow * lda + lcol;
;   const bf16_t* bg = Bt + (size_t)lrow * ldb + lcol;
;   const char* A8 = (const char*)A;
;   const char* B8 = (const char*)Bt;
;   unsigned aoff[4], boff[NT];
; #pragma unroll
;   for (int i = 0; i < 4; ++i) aoff[i] = (unsigned)(((lrow + 32 * i) * lda + lcol) * 2);
; #pragma unroll
;   for (int i = 0; i < NT; ++i) boff[i] = (unsigned)(((lrow + (i & 1) * bs1 + (i >> 1) * bs2) * ldb + lcol) * 2);
;   const int wbase = __builtin_amdgcn_readfirstlane(wid) * 1024;
;   const int inner = frag_off(fr, fq);
;   const int abase = wr * 8192 + inner;
;   const int bbase = 16384 + wc * (NT * 2048) + inner;
;   const int nk = K >> 6;
; #pragma unroll
;   for (int i = 0; i < 4; ++i) __builtin_amdgcn_global_load_lds((const unsigned*)(ag + (size_t)(32 * i) * lda), (unsigned*)(smem + i * 4096 + o0), 16, 0, 0);
; #pragma unroll
;   for (int i = 0; i < NT; ++i) __builtin_amdgcn_global_load_lds((const unsigned*)(bg + (size_t)((i & 1) * bs1 + (i >> 1) * bs2) * ldb), (unsigned*)(smem + 16384 + i * 4096 + o0), 16, 0, 0);
;   asm volatile("s_waitcnt vmcnt(0)" ::: "memory");
;   __syncthreads();
; __device__ __forceinline__ void phase_win(const Params& p, char* smem, unsigned* tk) {
;     ...
;   for (TileIter ti(NTOK / 128, 25, 8, 5, tk); ti.valid();) {
;     int tm, tn; ti.get(tm, tn);
;     ti.prefetch();
;     f32x4 acc[4][4];
;     zero_acc<4>(acc);
;     gemm_main<4>(H + (size_t)tm * 128 * DM, DM, W + (size_t)tn * 128 * DM, DM, DM, acc, smem);
.LBB0_243:
	s_and_saveexec_b64 s[40:41], s[62:63]
	s_cbranch_execz .LBB0_247
	s_mov_b64 s[44:45], exec
	v_mbcnt_lo_u32_b32 v0, s44, 0
	v_mbcnt_hi_u32_b32 v0, s45, v0
	v_cmp_eq_u32_e32 vcc, 0, v0
	s_and_saveexec_b64 s[42:43], vcc
	s_cbranch_execz .LBB0_246
	s_bcnt1_i32_b64 s23, s[44:45]
	v_mov_b32_e32 v2, s23
	global_atomic_add v88, v1, v2, s[34:35] sc0
.LBB0_246:
	s_or_b64 exec, exec, s[42:43]
.LBB0_247:
	s_or_b64 exec, exec, s[40:41]
	s_mov_b32 s30, 0x66666667
	v_mul_hi_i32 v0, v70, s30
	v_lshrrev_b32_e32 v2, 31, v0
	v_ashrrev_i32_e32 v0, 4, v0
	v_add_u32_e32 v0, v0, v2
	s_movk_i32 s23, 0xffd8
	v_mad_u64_u32 v[2:3], s[40:41], v0, s23, v[70:71]
	v_lshl_or_b32 v0, v0, 3, s72
	v_mul_hi_i32 v3, v0, s30
	v_lshrrev_b32_e32 v4, 31, v3
	v_ashrrev_i32_e32 v3, 1, v3
	s_waitcnt vmcnt(1)
	v_add_u32_e32 v10, v3, v4
	v_mul_hi_i32 v3, v2, s30
	v_lshrrev_b32_e32 v4, 31, v3
	v_ashrrev_i32_e32 v3, 1, v3
	v_add_u32_e32 v11, v3, v4
	v_sub_u32_e32 v0, v0, v11
	v_mad_u64_u32 v[4:5], s[40:41], v10, -5, v[0:1]
	v_mov_b32_e32 v12, v172
	v_lshl_add_u32 v66, v10, 3, v11
	v_mad_u64_u32 v[68:69], s[40:41], v4, 5, v[2:3]
	v_ashrrev_i32_e32 v67, 31, v66
	s_waitcnt vmcnt(0)
	v_ashrrev_i32_e32 v14, 3, v12
	v_lshrrev_b32_e32 v0, 3, v12
	v_ashrrev_i32_e32 v69, 31, v68
	v_bfi_b32 v8, -8, v14, v0
	v_lshlrev_b64 v[2:3], 18, v[66:67]
	v_lshlrev_b64 v[6:7], 18, v[68:69]
	v_lshrrev_b32_e32 v0, 1, v8
	v_ashrrev_i32_e32 v9, 31, v8
	v_lshl_add_u64 v[4:5], v[92:93], 0, v[2:3]
	v_lshl_add_u64 v[6:7], v[124:125], 0, v[6:7]
	v_xor_b32_e32 v0, v0, v12
	v_lshlrev_b64 v[8:9], 11, v[8:9]
	v_and_b32_e32 v13, 15, v12
	v_lshlrev_b32_e32 v0, 3, v0
	v_lshl_add_u64 v[6:7], v[6:7], 0, v[8:9]
	v_lshl_add_u64 v[4:5], v[4:5], 0, v[8:9]
	v_lshlrev_b32_e32 v9, 3, v12
	v_and_b32_e32 v16, 56, v0
	v_lshlrev_b32_e32 v18, 4, v12
	v_lshlrev_b32_e32 v8, 7, v13
	v_and_b32_e32 v9, 0x70, v9
	v_and_b32_e32 v13, 48, v12
	v_lshlrev_b32_e32 v0, 1, v16
	v_ashrrev_i32_e32 v17, 6, v12
	v_bitop3_b32 v13, v9, v8, v13 bitop3:0xde
	v_lshlrev_b32_e32 v8, 6, v12
	v_readfirstlane_b32 s40, v18
	v_add_u32_e32 v19, 0x1000, v18
	v_bfe_u32 v15, v12, 3, 3
	v_lshl_add_u64 v[4:5], v[4:5], 0, v[0:1]
	v_and_b32_e32 v12, 0xffffe000, v8
	v_lshlrev_b32_e32 v8, 13, v17
	s_mov_b32 m0, s40
	v_readfirstlane_b32 s40, v19
	v_add_u32_e32 v19, 0x2000, v18
	v_readfirstlane_b32 s23, v17
	v_and_b32_e32 v17, 0x2000, v8
	global_load_lds_dwordx4 v[4:5], off
	v_lshl_add_u64 v[8:9], v[4:5], 0, s[4:5]
	s_mov_b32 m0, s40
	v_readfirstlane_b32 s40, v19
	global_load_lds_dwordx4 v[8:9], off
	v_lshl_add_u64 v[8:9], v[4:5], 0, s[6:7]
	s_mov_b32 m0, s40
	v_lshl_add_u64 v[4:5], v[4:5], 0, s[8:9]
	global_load_lds_dwordx4 v[8:9], off
	v_add_u32_e32 v8, 0x3000, v18
	v_or_b32_e32 v69, v13, v12
	v_readfirstlane_b32 s40, v8
	s_mov_b32 m0, s40
	v_add_u32_e32 v8, 0x5000, v18
	global_load_lds_dwordx4 v[4:5], off
	v_lshl_add_u64 v[4:5], v[6:7], 0, v[0:1]
	v_add_u32_e32 v6, 0x4000, v18
	v_bitop3_b32 v135, v13, 64, v12 bitop3:0x36
	v_readfirstlane_b32 s40, v6
	s_mov_b32 m0, s40
	v_readfirstlane_b32 s40, v8
	v_add_u32_e32 v8, 0x6000, v18
	global_load_lds_dwordx4 v[4:5], off
	v_lshl_add_u64 v[6:7], v[4:5], 0, s[4:5]
	s_mov_b32 m0, s40
	v_readfirstlane_b32 s40, v8
	global_load_lds_dwordx4 v[6:7], off
	v_lshl_add_u64 v[6:7], v[4:5], 0, s[6:7]
	s_mov_b32 m0, s40
	v_lshl_add_u64 v[4:5], v[4:5], 0, s[8:9]
	global_load_lds_dwordx4 v[6:7], off
	v_add_u32_e32 v6, 0x7000, v18
	v_or_b32_e32 v67, v13, v17
	v_readfirstlane_b32 s40, v6
	s_mov_b32 m0, s40
	v_lshrrev_b32_e32 v6, 3, v14
	global_load_lds_dwordx4 v[4:5], off
	v_lshlrev_b32_e32 v4, 14, v6
	v_lshlrev_b32_e32 v5, 11, v15
	v_or3_b32 v0, v4, v5, v0
	v_lshl_add_u64 v[4:5], v[2:3], 0, v[0:1]
	v_lshl_add_u64 v[72:73], v[126:127], 0, v[4:5]
	v_lshlrev_b32_e32 v4, 13, v6
	v_lshlrev_b32_e32 v5, 10, v15
	v_or3_b32 v4, v4, v5, v16
	v_lshlrev_b32_e32 v12, 1, v4
	v_add_u32_e32 v4, 0x10000, v12
	v_mov_b32_e32 v5, v1
	v_lshl_add_u64 v[6:7], v[2:3], 0, v[4:5]
	v_lshl_add_u64 v[74:75], v[126:127], 0, v[6:7]
	v_add_u32_e32 v6, 0x20000, v12
	v_mov_b32_e32 v7, v1
	v_lshl_add_u64 v[8:9], v[2:3], 0, v[6:7]
	v_lshl_add_u64 v[76:77], v[126:127], 0, v[8:9]
	v_add_u32_e32 v8, 0x30000, v12
	v_mov_b32_e32 v9, v1
	v_lshl_add_u64 v[2:3], v[2:3], 0, v[8:9]
	s_mul_i32 s40, s72, 5
	v_lshl_add_u64 v[78:79], v[126:127], 0, v[2:3]
	v_add_u32_e32 v2, s40, v70
	v_lshl_add_u32 v3, v11, 2, v11
	v_sub_u32_e32 v2, v2, v3
	v_mul_lo_u32 v3, v10, 25
	v_sub_u32_e32 v2, v2, v3
	v_ashrrev_i32_e32 v3, 31, v2
	v_lshlrev_b64 v[2:3], 18, v[2:3]
	v_lshl_add_u64 v[4:5], v[2:3], 0, v[4:5]
	s_waitcnt vmcnt(0)
	v_lshl_add_u64 v[10:11], v[2:3], 0, v[0:1]
	v_lshl_add_u64 v[80:81], v[130:131], 0, v[4:5]
	v_lshl_add_u64 v[4:5], v[2:3], 0, v[6:7]
	v_lshl_add_u64 v[2:3], v[2:3], 0, v[8:9]
	v_lshl_add_u64 v[84:85], v[130:131], 0, v[2:3]
	v_mov_b32_e32 v2, 0
	s_lshl_b32 s23, s23, 10
	v_bitop3_b32 v89, v13, 64, v17 bitop3:0x36
	v_lshl_add_u64 v[70:71], v[130:131], 0, v[10:11]
	v_lshl_add_u64 v[82:83], v[130:131], 0, v[4:5]
	s_mov_b64 s[40:41], 0
	s_mov_b32 s42, 0
	v_mov_b32_e32 v3, v2
	v_mov_b32_e32 v4, v2
	v_mov_b32_e32 v5, v2
	v_mov_b32_e32 v6, v2
	v_mov_b32_e32 v7, v2
	v_mov_b32_e32 v8, v2
	v_mov_b32_e32 v9, v2
	v_mov_b32_e32 v10, v2
	v_mov_b32_e32 v11, v2
	v_mov_b32_e32 v12, v2
	v_mov_b32_e32 v13, v2
	v_mov_b32_e32 v14, v2
	v_mov_b32_e32 v15, v2
	v_mov_b32_e32 v16, v2
	v_mov_b32_e32 v17, v2
	v_mov_b32_e32 v18, v2
	v_mov_b32_e32 v19, v2
	v_mov_b32_e32 v20, v2
	v_mov_b32_e32 v21, v2
	v_mov_b32_e32 v22, v2
	v_mov_b32_e32 v23, v2
	v_mov_b32_e32 v24, v2
	v_mov_b32_e32 v25, v2
	v_mov_b32_e32 v26, v2
	v_mov_b32_e32 v27, v2
	v_mov_b32_e32 v28, v2
	v_mov_b32_e32 v29, v2
	v_mov_b32_e32 v30, v2
	v_mov_b32_e32 v31, v2
	v_mov_b32_e32 v32, v2
	v_mov_b32_e32 v33, v2
	v_mov_b32_e32 v34, v2
	v_mov_b32_e32 v35, v2
	v_mov_b32_e32 v36, v2
	v_mov_b32_e32 v37, v2
	v_mov_b32_e32 v38, v2
	v_mov_b32_e32 v39, v2
	v_mov_b32_e32 v40, v2
	v_mov_b32_e32 v41, v2
	v_mov_b32_e32 v42, v2
	v_mov_b32_e32 v43, v2
	v_mov_b32_e32 v44, v2
	v_mov_b32_e32 v45, v2
	v_mov_b32_e32 v46, v2
	v_mov_b32_e32 v47, v2
	v_mov_b32_e32 v48, v2
	v_mov_b32_e32 v49, v2
	v_mov_b32_e32 v50, v2
	v_mov_b32_e32 v51, v2
	v_mov_b32_e32 v52, v2
	v_mov_b32_e32 v53, v2
	v_mov_b32_e32 v54, v2
	v_mov_b32_e32 v55, v2
	v_mov_b32_e32 v56, v2
	v_mov_b32_e32 v57, v2
	v_mov_b32_e32 v58, v2
	v_mov_b32_e32 v59, v2
	v_mov_b32_e32 v60, v2
	v_mov_b32_e32 v61, v2
	v_mov_b32_e32 v62, v2
	v_mov_b32_e32 v63, v2
	v_mov_b32_e32 v64, v2
	v_mov_b32_e32 v65, v2
	s_waitcnt vmcnt(0) lgkmcnt(0)
	s_barrier

; __device__ __forceinline__ int otid() { int t = threadIdx.x; asm volatile("" : "+v"(t)); return t; }
; __device__ __forceinline__ int frag_off(int fr, int fq) { return (fr >> 3) * 1024 + (fr & 7) * 128 + ((fq ^ ((fr >> 1) & 7)) << 4); }
;   const int tid = otid(), lane = tid & 63, wid = tid >> 6, wr = wid >> 1, wc = wid & 1, fr = lane & 15, fq = lane >> 4;
;   const int o0 = tid * 16;
;   const int lrow = (o0 >> 10) * 8 + ((o0 >> 7) & 7), lcol = ((((o0 >> 4) & 7) ^ ((lrow >> 1) & 7))) * 8;
;   const bf16_t* ag = A + (size_t)lrow * lda + lcol;
;   const bf16_t* bg = Bt + (size_t)lrow * ldb + lcol;
;   const char* A8 = (const char*)A;
;   const char* B8 = (const char*)Bt;
;   unsigned aoff[4], boff[NT];
; #pragma unroll
;   for (int i = 0; i < 4; ++i) aoff[i] = (unsigned)(((lrow + 32 * i) * lda + lcol) * 2);
; #pragma unroll
;   for (int i = 0; i < NT; ++i) boff[i] = (unsigned)(((lrow + (i & 1) * bs1 + (i >> 1) * bs2) * ldb + lcol) * 2);
;   const int wbase = __builtin_amdgcn_readfirstlane(wid) * 1024;
;   const int inner = frag_off(fr, fq);
;   const int abase = wr * 8192 + inner;
;   const int bbase = 16384 + wc * (NT * 2048) + inner;
;   const int nk = K >> 6;
; #pragma unroll
;   for (int i = 0; i < 4; ++i) __builtin_amdgcn_global_load_lds((const unsigned*)(ag + (size_t)(32 * i) * lda), (unsigned*)(smem + i * 4096 + o0), 16, 0, 0);
; #pragma unroll
;   for (int i = 0; i < NT; ++i) __builtin_amdgcn_global_load_lds((const unsigned*)(bg + (size_t)((i & 1) * bs1 + (i >> 1) * bs2) * ldb), (unsigned*)(smem + 16384 + i * 4096 + o0), 16, 0, 0);
;   asm volatile("s_waitcnt vmcnt(0)" ::: "memory");
;   __syncthreads();
; __device__ __forceinline__ void phase_resid_gemm(const Params& p, const bf16_t* A, int lda, const bf16_t* Wt, int K, int l, int gate_k, float scale,
;                                  bool from_input, int mrows, char* smem, unsigned* tk) {
;     ...
;   for (TileIter ti(mrows / 128, 8, 4, 8, tk); ti.valid();) {
;     int tm, tn; ti.get(tm, tn);
;     ti.prefetch();
;     f32x4 acc[4][4];
;     zero_acc<4>(acc);
;     gemm_main<4>(A + (size_t)tm * 128 * lda, lda, Wt + (size_t)tn * 128 * K, K, K, acc, smem);
.LBB0_295:
	s_and_saveexec_b64 s[40:41], s[62:63]
	s_cbranch_execz .LBB0_299
	s_mov_b64 s[56:57], exec
	v_mbcnt_lo_u32_b32 v0, s56, 0
	v_mbcnt_hi_u32_b32 v0, s57, v0
	v_cmp_eq_u32_e32 vcc, 0, v0
	s_and_saveexec_b64 s[42:43], vcc
	s_cbranch_execz .LBB0_298
	s_bcnt1_i32_b64 s53, s[56:57]
	v_mov_b32_e32 v2, s53
	global_atomic_add v135, v1, v2, s[36:37] sc0
.LBB0_298:
	s_or_b64 exec, exec, s[42:43]
.LBB0_299:
	s_or_b64 exec, exec, s[40:41]
	v_ashrrev_i32_e32 v0, 31, v138
	v_lshrrev_b32_e32 v0, 27, v0
	v_add_u32_e32 v0, v138, v0
	s_waitcnt vmcnt(2)
	v_and_b32_e32 v8, 0xffffffe0, v0
	v_sub_u32_e32 v0, v138, v8
	v_ashrrev_i32_e32 v2, 31, v0
	v_lshrrev_b32_e32 v2, 29, v2
	v_add_u32_e32 v2, v0, v2
	v_ashrrev_i32_e32 v9, 3, v2
	v_and_b32_e32 v2, -8, v2
	s_waitcnt vmcnt(1)
	v_mov_b32_e32 v10, v172
	v_or_b32_e32 v3, s75, v8
	v_sub_u32_e32 v136, v0, v2
	v_add_u32_e32 v137, v3, v9
	v_ashrrev_i32_e32 v0, 3, v10
	v_lshrrev_b32_e32 v6, 3, v10
	v_bfi_b32 v12, -8, v0, v6
	v_mad_i64_i32 v[2:3], s[40:41], s64, v137, 0
	v_mad_i64_i32 v[4:5], s[40:41], s64, v136, 0
	v_mad_i64_i32 v[6:7], s[40:41], v12, s60, 0
	v_lshl_add_u64 v[2:3], v[2:3], 1, v[68:69]
	v_lshl_add_u64 v[4:5], v[4:5], 1, v[70:71]
	v_lshrrev_b32_e32 v13, 1, v12
	v_lshlrev_b64 v[6:7], 1, v[6:7]
	v_and_b32_e32 v11, 15, v10
	v_xor_b32_e32 v0, v13, v10
	v_lshl_add_u64 v[4:5], v[4:5], 0, v[6:7]
	v_lshl_add_u64 v[2:3], v[2:3], 0, v[6:7]
	v_lshlrev_b32_e32 v7, 3, v10
	v_lshlrev_b32_e32 v0, 4, v0
	s_waitcnt vmcnt(0)
	v_lshlrev_b32_e32 v15, 4, v10
	v_lshlrev_b32_e32 v6, 7, v11
	v_and_b32_e32 v7, 0x70, v7
	v_and_b32_e32 v11, 48, v10
	v_ashrrev_i32_e32 v14, 6, v10
	v_and_b32_e32 v0, 0x70, v0
	v_bitop3_b32 v11, v7, v6, v11 bitop3:0xde
	v_lshlrev_b32_e32 v6, 6, v10
	v_readfirstlane_b32 s41, v15
	v_add_u32_e32 v17, 0x1000, v15
	v_lshl_add_u64 v[2:3], v[2:3], 0, v[0:1]
	v_and_b32_e32 v16, 0xffffe000, v6
	v_lshlrev_b32_e32 v6, 13, v14
	s_mov_b32 m0, s41
	v_readfirstlane_b32 s41, v17
	v_add_u32_e32 v17, 0x2000, v15
	v_readfirstlane_b32 s40, v14
	v_and_b32_e32 v14, 0x2000, v6
	global_load_lds_dwordx4 v[2:3], off
	v_lshl_add_u64 v[6:7], v[2:3], 0, s[98:99]
	s_mov_b32 m0, s41
	s_mov_b32 s53, s99
	v_readfirstlane_b32 s41, v17
	global_load_lds_dwordx4 v[6:7], off
	v_lshl_add_u64 v[6:7], v[2:3], 0, s[52:53]
	s_mov_b32 m0, s41
	s_mov_b32 s55, s99
	global_load_lds_dwordx4 v[6:7], off
	v_add_u32_e32 v6, 0x3000, v15
	v_lshl_add_u64 v[2:3], v[2:3], 0, s[54:55]
	v_readfirstlane_b32 s41, v6
	s_mov_b32 m0, s41
	v_add_u32_e32 v6, 0x5000, v15
	global_load_lds_dwordx4 v[2:3], off
	v_lshl_add_u64 v[2:3], v[4:5], 0, v[0:1]
	v_add_u32_e32 v4, 0x4000, v15
	v_or_b32_e32 v138, v11, v14
	v_readfirstlane_b32 s41, v4
	s_mov_b32 m0, s41
	v_readfirstlane_b32 s41, v6
	v_add_u32_e32 v6, 0x6000, v15
	global_load_lds_dwordx4 v[2:3], off
	v_lshl_add_u64 v[4:5], v[2:3], 0, s[98:99]
	s_mov_b32 m0, s41
	v_readfirstlane_b32 s41, v6
	global_load_lds_dwordx4 v[4:5], off
	v_lshl_add_u64 v[4:5], v[2:3], 0, s[52:53]
	s_mov_b32 m0, s41
	v_lshl_add_u64 v[2:3], v[2:3], 0, s[54:55]
	global_load_lds_dwordx4 v[4:5], off
	v_add_u32_e32 v4, 0x7000, v15
	v_or_b32_e32 v0, v11, v16
	v_readfirstlane_b32 s41, v4
	s_mov_b32 m0, s41
	v_add3_u32 v4, s75, v9, v8
	global_load_lds_dwordx4 v[2:3], off
	v_mov_b64_e32 v[2:3], s[46:47]
	v_mad_i64_i32 v[2:3], s[42:43], s67, v4, v[2:3]
	v_bitop3_b32 v4, v13, 7, v10 bitop3:0x48
	v_lshlrev_b32_e32 v4, 4, v4
	v_mad_u64_u32 v[6:7], s[42:43], s68, v12, v[4:5]
	v_add_u32_e32 v5, 32, v12
	v_mad_u64_u32 v[8:9], s[42:43], s68, v5, v[4:5]
	v_add_u32_e32 v5, 64, v12
	v_bitop3_b32 v140, v11, 64, v16 bitop3:0x36
	v_bitop3_b32 v139, v11, 64, v14 bitop3:0x36
	v_mad_u64_u32 v[10:11], s[42:43], s68, v5, v[4:5]
	v_add_u32_e32 v5, 0x60, v12
	v_mad_u64_u32 v[4:5], s[42:43], s68, v5, v[4:5]
	v_mov_b32_e32 v7, v1
	v_mov_b32_e32 v9, v1
	v_mov_b32_e32 v11, v1
	v_mov_b32_e32 v5, v1
	v_lshl_add_u64 v[72:73], v[2:3], 0, v[6:7]
	v_lshl_add_u64 v[74:75], v[2:3], 0, v[8:9]
	v_lshl_add_u64 v[76:77], v[2:3], 0, v[10:11]
	v_lshl_add_u64 v[78:79], v[2:3], 0, v[4:5]
	v_mov_b64_e32 v[2:3], s[48:49]
	s_waitcnt vmcnt(0)
	v_mad_i64_i32 v[2:3], s[42:43], s67, v136, v[2:3]
	v_lshl_add_u64 v[80:81], v[2:3], 0, v[6:7]
	v_lshl_add_u64 v[82:83], v[2:3], 0, v[8:9]
	v_lshl_add_u64 v[84:85], v[2:3], 0, v[10:11]
	v_lshl_add_u64 v[86:87], v[2:3], 0, v[4:5]
	v_mov_b32_e32 v2, 0
	s_lshl_b32 s40, s40, 10
	s_mov_b32 s41, 0
	s_mov_b32 s42, 0
	v_mov_b32_e32 v3, v2
	v_mov_b32_e32 v4, v2
	v_mov_b32_e32 v5, v2
	v_mov_b32_e32 v6, v2
	v_mov_b32_e32 v7, v2
	v_mov_b32_e32 v8, v2
	v_mov_b32_e32 v9, v2
	v_mov_b32_e32 v10, v2
	v_mov_b32_e32 v11, v2
	v_mov_b32_e32 v12, v2
	v_mov_b32_e32 v13, v2
	v_mov_b32_e32 v14, v2
	v_mov_b32_e32 v15, v2
	v_mov_b32_e32 v16, v2
	v_mov_b32_e32 v17, v2
	v_mov_b32_e32 v18, v2
	v_mov_b32_e32 v19, v2
	v_mov_b32_e32 v20, v2
	v_mov_b32_e32 v21, v2
	v_mov_b32_e32 v22, v2
	v_mov_b32_e32 v23, v2
	v_mov_b32_e32 v24, v2
	v_mov_b32_e32 v25, v2
	v_mov_b32_e32 v26, v2
	v_mov_b32_e32 v27, v2
	v_mov_b32_e32 v28, v2
	v_mov_b32_e32 v29, v2
	v_mov_b32_e32 v30, v2
	v_mov_b32_e32 v31, v2
	v_mov_b32_e32 v32, v2
	v_mov_b32_e32 v33, v2
	v_mov_b32_e32 v34, v2
	v_mov_b32_e32 v35, v2
	v_mov_b32_e32 v36, v2
	v_mov_b32_e32 v37, v2
	v_mov_b32_e32 v38, v2
	v_mov_b32_e32 v39, v2
	v_mov_b32_e32 v40, v2
	v_mov_b32_e32 v41, v2
	v_mov_b32_e32 v42, v2
	v_mov_b32_e32 v43, v2
	v_mov_b32_e32 v44, v2
	v_mov_b32_e32 v45, v2
	v_mov_b32_e32 v46, v2
	v_mov_b32_e32 v47, v2
	v_mov_b32_e32 v48, v2
	v_mov_b32_e32 v49, v2
	v_mov_b32_e32 v50, v2
	v_mov_b32_e32 v51, v2
	v_mov_b32_e32 v52, v2
	v_mov_b32_e32 v53, v2
	v_mov_b32_e32 v54, v2
	v_mov_b32_e32 v55, v2
	v_mov_b32_e32 v56, v2
	v_mov_b32_e32 v57, v2
	v_mov_b32_e32 v58, v2
	v_mov_b32_e32 v59, v2
	v_mov_b32_e32 v60, v2
	v_mov_b32_e32 v61, v2
	v_mov_b32_e32 v62, v2
	v_mov_b32_e32 v63, v2
	v_mov_b32_e32 v64, v2
	v_mov_b32_e32 v65, v2
	s_waitcnt vmcnt(0) lgkmcnt(0)
	s_barrier

; __device__ __forceinline__ int otid() { int t = threadIdx.x; asm volatile("" : "+v"(t)); return t; }
; __device__ __forceinline__ int frag_off(int fr, int fq) { return (fr >> 3) * 1024 + (fr & 7) * 128 + ((fq ^ ((fr >> 1) & 7)) << 4); }
;   const int tid = otid(), lane = tid & 63, wid = tid >> 6, wr = wid >> 1, wc = wid & 1, fr = lane & 15, fq = lane >> 4;
;   const int o0 = tid * 16;
;   const int lrow = (o0 >> 10) * 8 + ((o0 >> 7) & 7), lcol = ((((o0 >> 4) & 7) ^ ((lrow >> 1) & 7))) * 8;
;   const bf16_t* ag = A + (size_t)lrow * lda + lcol;
;   const bf16_t* bg = Bt + (size_t)lrow * ldb + lcol;
;   const char* A8 = (const char*)A;
;   const char* B8 = (const char*)Bt;
;   unsigned aoff[4], boff[NT];
; #pragma unroll
;   for (int i = 0; i < 4; ++i) aoff[i] = (unsigned)(((lrow + 32 * i) * lda + lcol) * 2);
; #pragma unroll
;   for (int i = 0; i < NT; ++i) boff[i] = (unsigned)(((lrow + (i & 1) * bs1 + (i >> 1) * bs2) * ldb + lcol) * 2);
;   const int wbase = __builtin_amdgcn_readfirstlane(wid) * 1024;
;   const int inner = frag_off(fr, fq);
;   const int abase = wr * 8192 + inner;
;   const int bbase = 16384 + wc * (NT * 2048) + inner;
;   const int nk = K >> 6;
; #pragma unroll
;   for (int i = 0; i < 4; ++i) __builtin_amdgcn_global_load_lds((const unsigned*)(ag + (size_t)(32 * i) * lda), (unsigned*)(smem + i * 4096 + o0), 16, 0, 0);
; #pragma unroll
;   for (int i = 0; i < NT; ++i) __builtin_amdgcn_global_load_lds((const unsigned*)(bg + (size_t)((i & 1) * bs1 + (i >> 1) * bs2) * ldb), (unsigned*)(smem + 16384 + i * 4096 + o0), 16, 0, 0);
;   asm volatile("s_waitcnt vmcnt(0)" ::: "memory");
;   __syncthreads();
; __device__ __forceinline__ void phase_ffn_up(const Params& p, int half, int mrows, char* smem, unsigned* tk) {
;     ...
;   for (TileIter ti(mrows / 128, 44, 4, 11, tk); ti.valid();) {
;     int tm, tn; ti.get(tm, tn);
;     ti.prefetch();
;     f32x4 acc[4][4];
;     zero_acc<4>(acc);
;     gemm_main<4>(H + (size_t)tm * 128 * DM, DM, W + (size_t)tn * 128 * DM, DM, DM, acc, smem);
.LBB0_320:
	s_and_saveexec_b64 s[42:43], s[62:63]
	s_cbranch_execz .LBB0_324
	s_mov_b64 s[48:49], exec
	v_mbcnt_lo_u32_b32 v2, s48, 0
	v_mbcnt_hi_u32_b32 v2, s49, v2
	v_cmp_eq_u32_e32 vcc, 0, v2
	s_and_saveexec_b64 s[46:47], vcc
	s_cbranch_execz .LBB0_323
	s_bcnt1_i32_b64 s48, s[48:49]
	v_mov_b32_e32 v3, s48
	global_atomic_add v138, v1, v3, s[36:37] sc0
.LBB0_323:
	s_or_b64 exec, exec, s[46:47]
.LBB0_324:
	s_or_b64 exec, exec, s[42:43]
	v_mul_hi_i32 v2, v72, s33
	v_lshrrev_b32_e32 v3, 31, v2
	v_ashrrev_i32_e32 v2, 3, v2
	s_waitcnt vmcnt(1)
	v_add_u32_e32 v12, v2, v3
	s_movk_i32 s42, 0xffd4
	v_mad_u64_u32 v[2:3], s[42:43], v12, s42, v[72:73]
	v_lshlrev_b32_e32 v3, 3, v12
	v_bfe_i32 v4, v12, 28, 1
	v_or_b32_e32 v3, s72, v3
	v_lshrrev_b32_e32 v4, 30, v4
	v_mul_hi_i32 v5, v2, s33
	v_add_u32_e32 v4, v3, v4
	v_lshrrev_b32_e32 v6, 31, v5
	v_ashrrev_i32_e32 v5, 1, v5
	s_waitcnt vmcnt(0)
	v_mov_b32_e32 v15, v172
	v_lshrrev_b32_e32 v13, 2, v4
	v_and_b32_e32 v4, -4, v4
	v_add_u32_e32 v14, v5, v6
	v_add_u32_e32 v74, v4, v14
	v_ashrrev_i32_e32 v17, 3, v15
	v_lshrrev_b32_e32 v8, 3, v15
	v_bfi_b32 v8, -8, v17, v8
	v_sub_u32_e32 v3, v3, v74
	v_lshrrev_b32_e32 v9, 1, v8
	v_mad_u64_u32 v[76:77], s[42:43], v3, 11, v[2:3]
	v_xor_b32_e32 v9, v9, v15
	v_ashrrev_i32_e32 v75, 31, v74
	v_ashrrev_i32_e32 v77, 31, v76
	v_lshlrev_b32_e32 v9, 3, v9
	v_lshlrev_b64 v[2:3], 18, v[74:75]
	v_lshlrev_b64 v[6:7], 18, v[76:77]
	v_and_b32_e32 v19, 56, v9
	v_ashrrev_i32_e32 v9, 31, v8
	v_lshl_add_u64 v[4:5], v[92:93], 0, v[2:3]
	v_lshl_add_u64 v[6:7], v[66:67], 0, v[6:7]
	v_lshlrev_b64 v[8:9], 11, v[8:9]
	v_and_b32_e32 v16, 15, v15
	v_lshl_add_u64 v[6:7], v[6:7], 0, v[8:9]
	v_lshl_add_u64 v[4:5], v[4:5], 0, v[8:9]
	v_lshlrev_b32_e32 v9, 3, v15
	v_lshlrev_b32_e32 v21, 4, v15
	v_lshlrev_b32_e32 v8, 7, v16
	v_and_b32_e32 v9, 0x70, v9
	v_and_b32_e32 v16, 48, v15
	v_lshlrev_b32_e32 v10, 1, v19
	v_ashrrev_i32_e32 v20, 6, v15
	v_mov_b32_e32 v11, v1
	v_bitop3_b32 v16, v9, v8, v16 bitop3:0xde
	v_lshlrev_b32_e32 v8, 6, v15
	v_readfirstlane_b32 s43, v21
	v_add_u32_e32 v22, 0x1000, v21
	v_bfe_u32 v18, v15, 3, 3
	v_lshl_add_u64 v[4:5], v[4:5], 0, v[10:11]
	v_and_b32_e32 v15, 0xffffe000, v8
	v_lshlrev_b32_e32 v8, 13, v20
	s_mov_b32 m0, s43
	v_readfirstlane_b32 s43, v22
	v_add_u32_e32 v22, 0x2000, v21
	v_readfirstlane_b32 s42, v20
	v_and_b32_e32 v20, 0x2000, v8
	global_load_lds_dwordx4 v[4:5], off
	v_lshl_add_u64 v[8:9], v[4:5], 0, s[4:5]
	s_mov_b32 m0, s43
	v_readfirstlane_b32 s43, v22
	global_load_lds_dwordx4 v[8:9], off
	v_lshl_add_u64 v[8:9], v[4:5], 0, s[6:7]
	s_mov_b32 m0, s43
	v_lshl_add_u64 v[4:5], v[4:5], 0, s[8:9]
	global_load_lds_dwordx4 v[8:9], off
	v_add_u32_e32 v8, 0x3000, v21
	v_or_b32_e32 v75, v16, v15
	v_readfirstlane_b32 s43, v8
	s_mov_b32 m0, s43
	v_add_u32_e32 v8, 0x5000, v21
	global_load_lds_dwordx4 v[4:5], off
	v_lshl_add_u64 v[4:5], v[6:7], 0, v[10:11]
	v_add_u32_e32 v6, 0x4000, v21
	v_bitop3_b32 v139, v16, 64, v15 bitop3:0x36
	v_readfirstlane_b32 s43, v6
	s_mov_b32 m0, s43
	v_readfirstlane_b32 s43, v8
	v_add_u32_e32 v8, 0x6000, v21
	global_load_lds_dwordx4 v[4:5], off
	v_lshl_add_u64 v[6:7], v[4:5], 0, s[4:5]
	s_mov_b32 m0, s43
	v_readfirstlane_b32 s43, v8
	global_load_lds_dwordx4 v[6:7], off
	v_lshl_add_u64 v[6:7], v[4:5], 0, s[6:7]
	s_mov_b32 m0, s43
	v_lshl_add_u64 v[4:5], v[4:5], 0, s[8:9]
	global_load_lds_dwordx4 v[6:7], off
	v_add_u32_e32 v6, 0x7000, v21
	v_lshrrev_b32_e32 v8, 3, v17
	v_readfirstlane_b32 s43, v6
	s_mov_b32 m0, s43
	s_lshl_b32 s46, s42, 10
	global_load_lds_dwordx4 v[4:5], off
	v_lshlrev_b32_e32 v4, 14, v8
	v_lshlrev_b32_e32 v5, 11, v18
	v_or3_b32 v4, v4, v5, v10
	v_mov_b32_e32 v5, v1
	v_lshl_add_u64 v[6:7], v[2:3], 0, v[4:5]
	v_lshl_add_u64 v[78:79], v[126:127], 0, v[6:7]
	v_lshlrev_b32_e32 v6, 13, v8
	v_lshlrev_b32_e32 v7, 10, v18
	v_or3_b32 v6, v6, v7, v19
	v_lshlrev_b32_e32 v15, 1, v6
	v_add_u32_e32 v6, 0x10000, v15
	v_mov_b32_e32 v7, v1
	v_lshl_add_u64 v[8:9], v[2:3], 0, v[6:7]
	v_lshl_add_u64 v[80:81], v[126:127], 0, v[8:9]
	v_add_u32_e32 v8, 0x20000, v15
	v_mov_b32_e32 v9, v1
	v_lshl_add_u64 v[10:11], v[2:3], 0, v[8:9]
	v_lshl_add_u64 v[82:83], v[126:127], 0, v[10:11]
	v_add_u32_e32 v10, 0x30000, v15
	v_mov_b32_e32 v11, v1
	v_lshl_add_u64 v[2:3], v[2:3], 0, v[10:11]
	v_lshl_add_u64 v[84:85], v[126:127], 0, v[2:3]
	v_mul_lo_u32 v2, v12, 44
	s_mul_i32 s42, s72, 11
	v_add3_u32 v2, s42, v72, v2
	v_mul_lo_u32 v3, v14, 11
	v_sub_u32_e32 v2, v2, v3
	v_mul_lo_u32 v3, v13, 44
	v_sub_u32_e32 v2, v2, v3
	v_ashrrev_i32_e32 v3, 31, v2
	v_lshlrev_b64 v[2:3], 18, v[2:3]
	v_lshl_add_u64 v[4:5], v[2:3], 0, v[4:5]
	v_lshl_add_u64 v[72:73], v[68:69], 0, v[4:5]
	v_lshl_add_u64 v[4:5], v[2:3], 0, v[6:7]
	s_waitcnt vmcnt(0)
	v_lshl_add_u64 v[86:87], v[68:69], 0, v[4:5]
	v_lshl_add_u64 v[4:5], v[2:3], 0, v[8:9]
	v_lshl_add_u64 v[2:3], v[2:3], 0, v[10:11]
	v_lshl_add_u64 v[136:137], v[68:69], 0, v[2:3]
	v_mov_b32_e32 v2, 0
	v_or_b32_e32 v71, v16, v20
	v_bitop3_b32 v77, v16, 64, v20 bitop3:0x36
	v_lshl_add_u64 v[88:89], v[68:69], 0, v[4:5]
	s_mov_b64 s[42:43], 0
	s_mov_b32 s47, 0
	v_mov_b32_e32 v3, v2
	v_mov_b32_e32 v4, v2
	v_mov_b32_e32 v5, v2
	v_mov_b32_e32 v6, v2
	v_mov_b32_e32 v7, v2
	v_mov_b32_e32 v8, v2
	v_mov_b32_e32 v9, v2
	v_mov_b32_e32 v10, v2
	v_mov_b32_e32 v11, v2
	v_mov_b32_e32 v12, v2
	v_mov_b32_e32 v13, v2
	v_mov_b32_e32 v14, v2
	v_mov_b32_e32 v15, v2
	v_mov_b32_e32 v16, v2
	v_mov_b32_e32 v17, v2
	v_mov_b32_e32 v18, v2
	v_mov_b32_e32 v19, v2
	v_mov_b32_e32 v20, v2
	v_mov_b32_e32 v21, v2
	v_mov_b32_e32 v22, v2
	v_mov_b32_e32 v23, v2
	v_mov_b32_e32 v24, v2
	v_mov_b32_e32 v25, v2
	v_mov_b32_e32 v26, v2
	v_mov_b32_e32 v27, v2
	v_mov_b32_e32 v28, v2
	v_mov_b32_e32 v29, v2
	v_mov_b32_e32 v30, v2
	v_mov_b32_e32 v31, v2
	v_mov_b32_e32 v32, v2
	v_mov_b32_e32 v33, v2
	v_mov_b32_e32 v34, v2
	v_mov_b32_e32 v35, v2
	v_mov_b32_e32 v36, v2
	v_mov_b32_e32 v37, v2
	v_mov_b32_e32 v38, v2
	v_mov_b32_e32 v39, v2
	v_mov_b32_e32 v40, v2
	v_mov_b32_e32 v41, v2
	v_mov_b32_e32 v42, v2
	v_mov_b32_e32 v43, v2
	v_mov_b32_e32 v44, v2
	v_mov_b32_e32 v45, v2
	v_mov_b32_e32 v46, v2
	v_mov_b32_e32 v47, v2
	v_mov_b32_e32 v48, v2
	v_mov_b32_e32 v49, v2
	v_mov_b32_e32 v50, v2
	v_mov_b32_e32 v51, v2
	v_mov_b32_e32 v52, v2
	v_mov_b32_e32 v53, v2
	v_mov_b32_e32 v54, v2
	v_mov_b32_e32 v55, v2
	v_mov_b32_e32 v56, v2
	v_mov_b32_e32 v57, v2
	v_mov_b32_e32 v58, v2
	v_mov_b32_e32 v59, v2
	v_mov_b32_e32 v60, v2
	v_mov_b32_e32 v61, v2
	v_mov_b32_e32 v62, v2
	v_mov_b32_e32 v63, v2
	v_mov_b32_e32 v64, v2
	v_mov_b32_e32 v65, v2
	s_waitcnt vmcnt(0) lgkmcnt(0)
	s_barrier
